# bh2 + conv section: loop-invariant weight-pointer loads hoisted out of the unit loop (v_cndmask select), pointer-load vmcnt waits dropped
# baseline (speedup 1.0000x reference)
; #define SUB(k, bit) (!(kargs()->li == 1 && (k) == lo) || ((kargs()->submask >> (bit)) & 1u))
; __global__ void __launch_bounds__(NWAVES * 64, 2) fwd(Args args_unused) {
;     ...
;         if (IN(pb + 3)) {
;             PH_PTRS PH_LAYER
;             if (SUB(pb + 3, 0)) {
;                 const int nitems = (M / 16) * 5;
; #pragma unroll 1
;                 for (int it = gw; it < nitems; it += NGW) {
;                     const int seg = it / 5, c = (it - seg * 5) * 64 + lane;
;                     if (c >= 192 && seg * 16 < NPROMPT) continue;
;                     const bool isB = c < 192; const int col = isB ? 8 * c : 8 * (c - 192); const int zc = isB ? ZXBC + col : ZXC + col; const int nch = isB ? 1536 : 1024;
;                     const float* cwp = (isB ? A->in[I_CBW] + (size_t)l * 4 * 1536 : A->in[I_CCW] + (size_t)l * 4 * 1024) + col;
;                     const float* cbp = (isB ? A->in[I_CBB] + (size_t)l * 1536 : A->in[I_CCB] + (size_t)l * 1024) + col;
.Lro_again_0:
	s_cmp_lt_i32 s84, 7
	s_cselect_b64 s[0:1], -1, 0
	s_cmp_gt_i32 s85, 6
	s_waitcnt lgkmcnt(0)
	s_cselect_b64 s[4:5], -1, 0
	s_and_b64 s[0:1], s[0:1], s[4:5]
	s_andn2_b64 vcc, exec, s[0:1]
	s_cbranch_vccnz .LBB0_1520
	s_mov_b64 s[26:27], s[82:83]
	s_load_dwordx2 s[28:29], s[26:27], 0x148
	s_mov_b32 s62, 0
	s_load_dword s64, s[82:83], 0x168
	v_readlane_b32 s33, v254, 3
	s_mov_b32 s3, s2
	v_mov_b32_e32 v1, v0
	s_waitcnt lgkmcnt(0)
	s_lshl_b32 s4, s33, 3
	v_readfirstlane_b32 s61, v1
	s_ashr_i32 s63, s61, 6
	s_lshl_b32 s3, s64, 3
	s_add_i32 s60, s63, s4
	s_add_u32 s30, s28, 0x1d200000
	s_addc_u32 s31, s29, 0
	s_cmpk_gt_i32 s60, 0x284f
	v_and_b32_e32 v130, 63, v1
	s_cselect_b32 s99, 1, 0
	s_cmp_eq_u32 s98, 0
	s_cbranch_scc1 .LBB0_1477
	s_cmp_lg_u32 s99, 0
	s_cbranch_scc1 .LBB0_1477
	s_add_u32 s8, s28, 0x4d800000
	s_addc_u32 s9, s29, 0
	s_add_u32 s10, s28, 0x53900000
	s_addc_u32 s11, s29, 0
	s_lshl_b32 s4, s33, 9
	s_lshl_b32 s5, s63, 6
	s_add_i32 s4, s4, s5
	v_or_b32_e32 v131, s4, v130
	v_lshlrev_b32_e32 v140, 3, v131
	s_lshl_b32 s65, s64, 12
	s_lshl_b32 s66, s64, 9
	s_movk_i32 s67, 0xc0
	s_movk_i32 s68, 0xbf
	v_mov_b32_e32 v133, 0
	v_mov_b32_e32 v141, 0x400
	v_mov_b32_e32 v142, 0x600
	v_mov_b32_e32 v143, 0x1c00
	v_mov_b32_e32 v144, 0x1600
	v_mov_b32_e32 v145, 0xd8
	v_mov_b32_e32 v146, 0xa0
	v_mov_b32_e32 v147, 0xe0
	v_mov_b32_e32 v148, 0xa8
	v_mov_b32_e32 v149, 0xc00
	global_load_dwordx2 v[244:245], v133, s[26:27] offset:216
	global_load_dwordx2 v[246:247], v133, s[26:27] offset:160
	global_load_dwordx2 v[248:249], v133, s[26:27] offset:224
	global_load_dwordx2 v[250:251], v133, s[26:27] offset:168
	s_waitcnt vmcnt(0)
	s_mov_b32 s69, s60
	s_branch .LBB0_1368

; __device__ __forceinline__ void unpack8(const v4u w, float (&o)[8]) { o[0] = bflo(w.x); o[1] = bfhi(w.x); o[2] = bflo(w.y); o[3] = bfhi(w.y); o[4] = bflo(w.z); o[5] = bfhi(w.z); o[6] = bflo(w.w); o[7] = bfhi(w.w); }
; __global__ void __launch_bounds__(NWAVES * 64, 2) fwd(Args args_unused) {
;     ...
;                     const int seg = it / 5, c = (it - seg * 5) * 64 + lane;
;                     if (c >= 192 && seg * 16 < NPROMPT) continue;
;                     const bool isB = c < 192; const int col = isB ? 8 * c : 8 * (c - 192); const int zc = isB ? ZXBC + col : ZXC + col; const int nch = isB ? 1536 : 1024;
;                     const float* cwp = (isB ? A->in[I_CBW] + (size_t)l * 4 * 1536 : A->in[I_CCW] + (size_t)l * 4 * 1024) + col;
;                     const float* cbp = (isB ? A->in[I_CBB] + (size_t)l * 1536 : A->in[I_CCB] + (size_t)l * 1024) + col;
;                     float cw[4][8], cb[8];
; #pragma unroll
;                     for (int e = 0; e < 8; ++e) { cb[e] = cbp[e];
; #pragma unroll
;                         for (int j = 0; j < 4; ++j) cw[j][e] = cwp[j * nch + e]; }
;                     const int r0 = seg * 16; const bool isS = r0 >= NPROMPT; const int t0 = isS ? 0 : (r0 & (SEQ - 1));
;                     float win[3][8];
; #pragma unroll
;                     for (int j = 0; j < 3; ++j) {
;                         if (!isS && t0 >= 3) { unpack8(*(const v4u*)ZP(Z, r0 - 3 + j, zc), win[j]); }
.LBB0_1368:
	s_mul_hi_i32 s4, s69, 0x66666667
	s_lshr_b32 s5, s4, 31
	s_ashr_i32 s6, s4, 1
	s_add_i32 s6, s6, s5
	s_mul_i32 s4, s6, 0xfffffec0
	v_add_u32_e32 v42, s4, v131
	s_cmpk_gt_i32 s69, 0x27ff
	v_cmp_gt_i32_e32 vcc, s67, v42
	s_cselect_b64 s[4:5], -1, 0
	s_or_b64 s[4:5], s[4:5], vcc
	s_and_saveexec_b64 s[12:13], s[4:5]
	s_cbranch_execz .LBB0_1367
	v_cmp_gt_i32_e32 vcc, s67, v42
	s_mul_i32 s4, s6, 0xfffff600
	v_add_u32_e32 v10, s4, v140
	v_cndmask_b32_e32 v132, v145, v146, vcc
	v_lshl_add_u64 v[2:3], s[26:27], 0, v[132:133]
	v_cndmask_b32_e32 v132, v147, v148, vcc
	v_lshl_add_u64 v[4:5], s[26:27], 0, v[132:133]
	v_cndmask_b32_e32 v6, v244, v246, vcc
	v_cndmask_b32_e32 v7, v245, v247, vcc
	v_cndmask_b32_e32 v8, v248, v250, vcc
	v_cndmask_b32_e32 v9, v249, v251, vcc
	v_add_u32_e32 v11, 0xfffffa00, v10
	v_cndmask_b32_e32 v136, v11, v10, vcc
	v_cndmask_b32_e32 v134, v141, v142, vcc
	v_ashrrev_i32_e32 v137, 31, v136
	v_mul_u32_u24_e32 v4, 3, v134
	v_lshlrev_b64 v[10:11], 2, v[136:137]
	v_mov_b32_e32 v3, v133
	v_mov_b32_e32 v5, v133
	v_lshlrev_b32_e32 v2, 3, v134
	v_lshlrev_b32_e32 v4, 2, v4
	v_lshlrev_b32_e32 v132, 2, v134
	s_lshl_b32 s34, s6, 4
	s_cmpk_gt_i32 s69, 0x27ff
	s_cselect_b64 s[54:55], -1, 0
	s_and_b32 s6, s6, 0x7f
	v_cmp_lt_i32_e64 s[4:5], s68, v42
	v_cndmask_b32_e32 v42, v143, v144, vcc
	s_cmp_eq_u32 s6, 0
	v_add_u32_e32 v42, v136, v42
	s_cselect_b64 s[6:7], -1, 0
	s_or_b64 s[6:7], s[54:55], s[6:7]
	v_lshrrev_b32_e32 v42, 8, v42
	v_mul_hi_i32_i24_e32 v43, 0x8100, v42
	v_mul_i32_i24_e32 v42, 0x8100, v42
	s_and_b64 vcc, exec, s[6:7]
	v_lshl_add_u64 v[6:7], v[6:7], 0, v[10:11]
	v_lshl_add_u64 v[44:45], v[8:9], 0, v[10:11]
	global_load_dwordx4 v[10:13], v[6:7], off offset:16
	global_load_dwordx4 v[26:29], v[6:7], off
	v_lshl_add_u64 v[46:47], v[6:7], 0, v[132:133]
	v_lshl_add_u64 v[48:49], v[6:7], 0, v[2:3]
	v_lshl_add_u64 v[50:51], v[6:7], 0, v[4:5]
	global_load_dwordx4 v[2:5], v[44:45], off offset:16
	global_load_dwordx4 v[6:9], v[44:45], off
	global_load_dwordx4 v[14:17], v[46:47], off offset:16
	global_load_dwordx4 v[30:33], v[46:47], off
	global_load_dwordx4 v[18:21], v[48:49], off offset:16
	global_load_dwordx4 v[34:37], v[48:49], off
	global_load_dwordx4 v[22:25], v[50:51], off offset:16
	global_load_dwordx4 v[38:41], v[50:51], off
	v_and_b32_e32 v44, 0xf8, v136
	v_lshlrev_b32_e32 v44, 1, v44
	v_mov_b32_e32 v45, v133
	v_lshl_add_u64 v[44:45], s[30:31], 0, v[44:45]
	s_cbranch_vccnz .LBB0_1371
	s_add_i32 s14, s34, -3
	s_ashr_i32 s15, s14, 31
	v_lshl_add_u64 v[46:47], v[42:43], 0, s[14:15]
	v_lshlrev_b64 v[46:47], 9, v[46:47]
	v_lshl_add_u64 v[46:47], v[44:45], 0, v[46:47]
	global_load_dwordx4 v[46:49], v[46:47], off
	s_waitcnt vmcnt(0)
	v_and_b32_e32 v123, 0xffff0000, v46
	v_lshlrev_b32_e32 v122, 16, v46
	v_and_b32_e32 v125, 0xffff0000, v47
	v_lshlrev_b32_e32 v124, 16, v47
	v_and_b32_e32 v119, 0xffff0000, v48
	v_lshlrev_b32_e32 v118, 16, v48
	v_and_b32_e32 v121, 0xffff0000, v49
	v_lshlrev_b32_e32 v120, 16, v49
	s_branch .LBB0_1372

; #define SUB(k, bit) (!(kargs()->li == 1 && (k) == lo) || ((kargs()->submask >> (bit)) & 1u))
; __global__ void __launch_bounds__(NWAVES * 64, 2) fwd(Args args_unused) {
;     ...
;         if (IN(pb + 3)) {
;             PH_PTRS PH_LAYER
;             if (SUB(pb + 3, 0)) {
;                 const int nitems = (M / 16) * 5;
; #pragma unroll 1
;                 for (int it = gw; it < nitems; it += NGW) {
;                     const int seg = it / 5, c = (it - seg * 5) * 64 + lane;
;                     if (c >= 192 && seg * 16 < NPROMPT) continue;
;                     const bool isB = c < 192; const int col = isB ? 8 * c : 8 * (c - 192); const int zc = isB ? ZXBC + col : ZXC + col; const int nch = isB ? 1536 : 1024;
;                     const float* cwp = (isB ? A->in[I_CBW] + (size_t)l * 4 * 1536 : A->in[I_CCW] + (size_t)l * 4 * 1024) + col;
;                     const float* cbp = (isB ? A->in[I_CBB] + (size_t)l * 1536 : A->in[I_CCB] + (size_t)l * 1024) + col;
.Lro_again_1:
	s_cmp_lt_i32 s84, 17
	s_cselect_b64 s[0:1], -1, 0
	s_cmp_gt_i32 s85, 16
	s_waitcnt lgkmcnt(0)
	s_cselect_b64 s[4:5], -1, 0
	s_and_b64 s[0:1], s[0:1], s[4:5]
	s_andn2_b64 vcc, exec, s[0:1]
	s_cbranch_vccnz .LBB0_3545
	s_mov_b64 s[26:27], s[82:83]
	s_load_dwordx2 s[28:29], s[26:27], 0x148
	s_mov_b32 s62, 0
	s_mov_b32 s3, s2
	s_load_dword s64, s[82:83], 0x168
	v_readlane_b32 s33, v254, 3
	v_mov_b32_e32 v1, v0
	s_waitcnt lgkmcnt(0)
	s_lshl_b32 s4, s33, 3
	v_readfirstlane_b32 s61, v1
	s_ashr_i32 s63, s61, 6
	s_lshl_b32 s3, s64, 3
	s_add_i32 s60, s63, s4
	s_add_u32 s30, s28, 0x1d200000
	s_addc_u32 s31, s29, 0
	s_cmpk_gt_i32 s60, 0x284f
	v_and_b32_e32 v130, 63, v1
	s_cselect_b32 s99, 1, 0
	s_cmp_eq_u32 s98, 0
	s_cbranch_scc1 .LBB0_3502
	s_cmp_lg_u32 s99, 0
	s_cbranch_scc1 .LBB0_3502
	s_add_u32 s8, s28, 0x4d800000
	s_addc_u32 s9, s29, 0
	s_add_u32 s10, s28, 0x53900000
	s_addc_u32 s11, s29, 0
	s_lshl_b32 s4, s33, 9
	s_lshl_b32 s5, s63, 6
	s_add_i32 s4, s4, s5
	v_or_b32_e32 v131, s4, v130
	v_lshlrev_b32_e32 v140, 3, v131
	s_lshl_b32 s65, s64, 12
	s_lshl_b32 s66, s64, 9
	s_movk_i32 s67, 0xc0
	s_movk_i32 s68, 0xbf
	v_mov_b32_e32 v133, 0
	v_mov_b32_e32 v141, 0x400
	v_mov_b32_e32 v142, 0x600
	v_mov_b32_e32 v143, 0x1c00
	v_mov_b32_e32 v144, 0x1600
	v_mov_b32_e32 v145, 0xd8
	v_mov_b32_e32 v146, 0xa0
	v_mov_b32_e32 v147, 0x4000
	v_mov_b32_e32 v148, 0x6000
	v_mov_b32_e32 v149, 0xe0
	v_mov_b32_e32 v150, 0xa8
	v_mov_b32_e32 v151, 0x1000
	v_mov_b32_e32 v152, 0x1800
	v_mov_b32_e32 v153, 0xc00
	global_load_dwordx2 v[244:245], v133, s[26:27] offset:216
	global_load_dwordx2 v[246:247], v133, s[26:27] offset:160
	global_load_dwordx2 v[248:249], v133, s[26:27] offset:224
	global_load_dwordx2 v[250:251], v133, s[26:27] offset:168
	s_waitcnt vmcnt(0)
	s_mov_b32 s69, s60
	s_branch .LBB0_3393

; __device__ __forceinline__ void unpack8(const v4u w, float (&o)[8]) { o[0] = bflo(w.x); o[1] = bfhi(w.x); o[2] = bflo(w.y); o[3] = bfhi(w.y); o[4] = bflo(w.z); o[5] = bfhi(w.z); o[6] = bflo(w.w); o[7] = bfhi(w.w); }
; __global__ void __launch_bounds__(NWAVES * 64, 2) fwd(Args args_unused) {
;     ...
;                     const int seg = it / 5, c = (it - seg * 5) * 64 + lane;
;                     if (c >= 192 && seg * 16 < NPROMPT) continue;
;                     const bool isB = c < 192; const int col = isB ? 8 * c : 8 * (c - 192); const int zc = isB ? ZXBC + col : ZXC + col; const int nch = isB ? 1536 : 1024;
;                     const float* cwp = (isB ? A->in[I_CBW] + (size_t)l * 4 * 1536 : A->in[I_CCW] + (size_t)l * 4 * 1024) + col;
;                     const float* cbp = (isB ? A->in[I_CBB] + (size_t)l * 1536 : A->in[I_CCB] + (size_t)l * 1024) + col;
;                     float cw[4][8], cb[8];
; #pragma unroll
;                     for (int e = 0; e < 8; ++e) { cb[e] = cbp[e];
; #pragma unroll
;                         for (int j = 0; j < 4; ++j) cw[j][e] = cwp[j * nch + e]; }
;                     const int r0 = seg * 16; const bool isS = r0 >= NPROMPT; const int t0 = isS ? 0 : (r0 & (SEQ - 1));
;                     float win[3][8];
; #pragma unroll
;                     for (int j = 0; j < 3; ++j) {
;                         if (!isS && t0 >= 3) { unpack8(*(const v4u*)ZP(Z, r0 - 3 + j, zc), win[j]); }
.LBB0_3393:
	s_mul_hi_i32 s4, s69, 0x66666667
	s_lshr_b32 s5, s4, 31
	s_ashr_i32 s6, s4, 1
	s_add_i32 s6, s6, s5
	s_mul_i32 s4, s6, 0xfffffec0
	v_add_u32_e32 v42, s4, v131
	s_cmpk_gt_i32 s69, 0x27ff
	v_cmp_gt_i32_e32 vcc, s67, v42
	s_cselect_b64 s[4:5], -1, 0
	s_or_b64 s[4:5], s[4:5], vcc
	s_and_saveexec_b64 s[12:13], s[4:5]
	s_cbranch_execz .LBB0_3392
	v_cmp_gt_i32_e32 vcc, s67, v42
	s_mul_i32 s4, s6, 0xfffff600
	v_add_u32_e32 v10, s4, v140
	v_cndmask_b32_e32 v132, v145, v146, vcc
	v_lshl_add_u64 v[2:3], s[26:27], 0, v[132:133]
	v_cndmask_b32_e32 v2, v244, v246, vcc
	v_cndmask_b32_e32 v3, v245, v247, vcc
	v_cndmask_b32_e32 v132, v147, v148, vcc
	v_add_u32_e32 v11, 0xfffffa00, v10
	v_cndmask_b32_e32 v136, v11, v10, vcc
	v_ashrrev_i32_e32 v137, 31, v136
	v_cndmask_b32_e32 v134, v141, v142, vcc
	v_lshlrev_b64 v[18:19], 2, v[136:137]
	v_mov_b32_e32 v7, v133
	v_lshlrev_b32_e32 v6, 3, v134
	v_mul_u32_u24_e32 v8, 3, v134
	v_mov_b32_e32 v9, v133
	v_lshlrev_b32_e32 v8, 2, v8
	s_lshl_b32 s34, s6, 4
	s_cmpk_gt_i32 s69, 0x27ff
	s_cselect_b64 s[54:55], -1, 0
	s_and_b32 s6, s6, 0x7f
	v_cmp_lt_i32_e64 s[4:5], s68, v42
	v_cndmask_b32_e32 v42, v143, v144, vcc
	s_cmp_eq_u32 s6, 0
	v_add_u32_e32 v42, v136, v42
	s_cselect_b64 s[6:7], -1, 0
	s_or_b64 s[6:7], s[54:55], s[6:7]
	v_lshrrev_b32_e32 v42, 8, v42
	v_mul_hi_i32_i24_e32 v43, 0x8100, v42
	v_mul_i32_i24_e32 v42, 0x8100, v42
	v_lshl_add_u64 v[2:3], v[2:3], 0, v[132:133]
	v_cndmask_b32_e32 v132, v149, v150, vcc
	v_lshl_add_u64 v[4:5], s[26:27], 0, v[132:133]
	v_cndmask_b32_e32 v4, v248, v250, vcc
	v_cndmask_b32_e32 v5, v249, v251, vcc
	v_cndmask_b32_e32 v132, v151, v152, vcc
	v_lshl_add_u64 v[2:3], v[2:3], 0, v[18:19]
	v_lshl_add_u64 v[6:7], v[2:3], 0, v[6:7]
	global_load_dwordx4 v[10:13], v[2:3], off offset:16
	global_load_dwordx4 v[26:29], v[2:3], off
	v_lshl_add_u64 v[44:45], v[2:3], 0, v[8:9]
	global_load_dwordx4 v[14:17], v[6:7], off offset:16
	global_load_dwordx4 v[30:33], v[6:7], off
	s_and_b64 vcc, exec, s[6:7]
	v_lshl_add_u64 v[4:5], v[4:5], 0, v[132:133]
	v_lshlrev_b32_e32 v132, 2, v134
	v_lshl_add_u64 v[46:47], v[4:5], 0, v[18:19]
	v_lshl_add_u64 v[48:49], v[2:3], 0, v[132:133]
	global_load_dwordx4 v[2:5], v[46:47], off offset:16
	global_load_dwordx4 v[6:9], v[46:47], off
	global_load_dwordx4 v[22:25], v[48:49], off offset:16
	global_load_dwordx4 v[38:41], v[48:49], off
	global_load_dwordx4 v[18:21], v[44:45], off offset:16
	global_load_dwordx4 v[34:37], v[44:45], off
	v_and_b32_e32 v44, 0xf8, v136
	v_lshlrev_b32_e32 v44, 1, v44
	v_mov_b32_e32 v45, v133
	v_lshl_add_u64 v[44:45], s[30:31], 0, v[44:45]
	s_cbranch_vccnz .LBB0_3396
	s_add_i32 s14, s34, -3
	s_ashr_i32 s15, s14, 31
	v_lshl_add_u64 v[46:47], v[42:43], 0, s[14:15]
	v_lshlrev_b64 v[46:47], 9, v[46:47]
	v_lshl_add_u64 v[46:47], v[44:45], 0, v[46:47]
	global_load_dwordx4 v[46:49], v[46:47], off
	s_waitcnt vmcnt(0)
	v_and_b32_e32 v123, 0xffff0000, v46
	v_lshlrev_b32_e32 v122, 16, v46
	v_and_b32_e32 v125, 0xffff0000, v47
	v_lshlrev_b32_e32 v124, 16, v47
	v_and_b32_e32 v119, 0xffff0000, v48
	v_lshlrev_b32_e32 v118, 16, v48
	v_and_b32_e32 v121, 0xffff0000, v49
	v_lshlrev_b32_e32 v120, 16, v49
	s_branch .LBB0_3397
